# context FNet unit moved from plain-VALU DFT loops to f32 matrix cores (v_mfma_f32_16x16x4_f32), f32 twiddles and f32 accumulate kept
# speedup vs baseline: 1.1282x; 1.0444x over previous
.LBB0_374:
	s_or_b64 exec, exec, s[6:7]
	s_movk_i32 s0, 0x2000
	s_and_b32 s8, s13, 1
	s_bfe_u32 s9, s13, 0x20003
	s_ashr_i32 s70, s13, 5
	v_cmp_gt_i32_e32 vcc, s0, v10
	v_and_b32_e32 v5, 31, v10
	s_waitcnt vmcnt(0) lgkmcnt(0)
	s_barrier
	s_lshr_b32 s0, s13, 5
	s_bfe_u32 s1, s13, 0x20003
	s_bfe_u32 s2, s13, 0x20001
	s_and_b32 s3, s13, 1
	v_and_b32_e32 v96, 63, v143
	v_lshrrev_b32_e32 v97, 6, v143
	v_and_b32_e32 v98, 15, v96
	v_lshrrev_b32_e32 v99, 4, v96
	s_lshl_b32 s6, s0, 8
	s_mul_i32 s6, s6, 0xe00
	s_lshl_b32 s7, s1, 7
	s_add_i32 s6, s6, s7
	s_add_u32 s6, s6, 0x5e00400
	s_add_u32 s6, s4, s6
	s_addc_u32 s7, s5, 0
	v_lshl_add_u32 v100, v97, 5, v98
	v_mul_u32_u24_e32 v100, 0xe00, v100
	v_lshl_add_u32 v100, v99, 5, v100
	global_load_dwordx4 v[0:3], v100, s[6:7] offset:0
	global_load_dwordx4 v[4:7], v100, s[6:7] offset:16
	s_add_u32 s6, s6, 0xe000
	s_addc_u32 s7, s7, 0
	global_load_dwordx4 v[8:11], v100, s[6:7] offset:0
	global_load_dwordx4 v[12:15], v100, s[6:7] offset:16
	s_lshl_b32 s8, s2, 4
	v_add_u32_e32 v101, s8, v98
	v_lshlrev_b32_e32 v102, 4, v99
	v_mul_u32_u24_e32 v102, v102, v101
	v_mov_b32_e32 v119, 0x10000
	v_and_b32_e32 v103, 63, v102
	v_lshl_add_u32 v103, v103, 2, v119
	ds_read_b32 v48, v103 offset:0
	ds_read_b32 v64, v103 offset:256
	v_add_u32_e32 v102, v102, v101
	v_and_b32_e32 v103, 63, v102
	v_lshl_add_u32 v103, v103, 2, v119
	ds_read_b32 v49, v103 offset:0
	ds_read_b32 v65, v103 offset:256
	v_add_u32_e32 v102, v102, v101
	v_and_b32_e32 v103, 63, v102
	v_lshl_add_u32 v103, v103, 2, v119
	ds_read_b32 v50, v103 offset:0
	ds_read_b32 v66, v103 offset:256
	v_add_u32_e32 v102, v102, v101
	v_and_b32_e32 v103, 63, v102
	v_lshl_add_u32 v103, v103, 2, v119
	ds_read_b32 v51, v103 offset:0
	ds_read_b32 v67, v103 offset:256
	v_add_u32_e32 v102, v102, v101
	v_and_b32_e32 v103, 63, v102
	v_lshl_add_u32 v103, v103, 2, v119
	ds_read_b32 v52, v103 offset:0
	ds_read_b32 v68, v103 offset:256
	v_add_u32_e32 v102, v102, v101
	v_and_b32_e32 v103, 63, v102
	v_lshl_add_u32 v103, v103, 2, v119
	ds_read_b32 v53, v103 offset:0
	ds_read_b32 v69, v103 offset:256
	v_add_u32_e32 v102, v102, v101
	v_and_b32_e32 v103, 63, v102
	v_lshl_add_u32 v103, v103, 2, v119
	ds_read_b32 v54, v103 offset:0
	ds_read_b32 v70, v103 offset:256
	v_add_u32_e32 v102, v102, v101
	s_waitcnt lgkmcnt(0)
	v_and_b32_e32 v103, 63, v102
	v_lshl_add_u32 v103, v103, 2, v119
	ds_read_b32 v55, v103 offset:0
	ds_read_b32 v71, v103 offset:256
	v_add_u32_e32 v102, v102, v101
	v_and_b32_e32 v103, 63, v102
	v_lshl_add_u32 v103, v103, 2, v119
	ds_read_b32 v56, v103 offset:0
	ds_read_b32 v72, v103 offset:256
	v_add_u32_e32 v102, v102, v101
	v_and_b32_e32 v103, 63, v102
	v_lshl_add_u32 v103, v103, 2, v119
	ds_read_b32 v57, v103 offset:0
	ds_read_b32 v73, v103 offset:256
	v_add_u32_e32 v102, v102, v101
	v_and_b32_e32 v103, 63, v102
	v_lshl_add_u32 v103, v103, 2, v119
	ds_read_b32 v58, v103 offset:0
	ds_read_b32 v74, v103 offset:256
	v_add_u32_e32 v102, v102, v101
	v_and_b32_e32 v103, 63, v102
	v_lshl_add_u32 v103, v103, 2, v119
	ds_read_b32 v59, v103 offset:0
	ds_read_b32 v75, v103 offset:256
	v_add_u32_e32 v102, v102, v101
	v_and_b32_e32 v103, 63, v102
	v_lshl_add_u32 v103, v103, 2, v119
	ds_read_b32 v60, v103 offset:0
	ds_read_b32 v76, v103 offset:256
	v_add_u32_e32 v102, v102, v101
	v_and_b32_e32 v103, 63, v102
	v_lshl_add_u32 v103, v103, 2, v119
	ds_read_b32 v61, v103 offset:0
	ds_read_b32 v77, v103 offset:256
	v_add_u32_e32 v102, v102, v101
	s_waitcnt lgkmcnt(0)
	v_and_b32_e32 v103, 63, v102
	v_lshl_add_u32 v103, v103, 2, v119
	ds_read_b32 v62, v103 offset:0
	ds_read_b32 v78, v103 offset:256
	v_add_u32_e32 v102, v102, v101
	v_and_b32_e32 v103, 63, v102
	v_lshl_add_u32 v103, v103, 2, v119
	ds_read_b32 v63, v103 offset:0
	ds_read_b32 v79, v103 offset:256
	s_waitcnt lgkmcnt(0)
	s_waitcnt vmcnt(2)
	v_lshlrev_b32_e32 v16, 16, v0
	v_and_b32_e32 v17, 0xffff0000, v0
	v_lshlrev_b32_e32 v18, 16, v1
	v_and_b32_e32 v19, 0xffff0000, v1
	v_lshlrev_b32_e32 v20, 16, v2
	v_and_b32_e32 v21, 0xffff0000, v2
	v_lshlrev_b32_e32 v22, 16, v3
	v_and_b32_e32 v23, 0xffff0000, v3
	v_lshlrev_b32_e32 v24, 16, v4
	v_and_b32_e32 v25, 0xffff0000, v4
	v_lshlrev_b32_e32 v26, 16, v5
	v_and_b32_e32 v27, 0xffff0000, v5
	v_lshlrev_b32_e32 v28, 16, v6
	v_and_b32_e32 v29, 0xffff0000, v6
	v_lshlrev_b32_e32 v30, 16, v7
	v_and_b32_e32 v31, 0xffff0000, v7
	s_waitcnt vmcnt(0)
	v_lshlrev_b32_e32 v32, 16, v8
	v_and_b32_e32 v33, 0xffff0000, v8
	v_lshlrev_b32_e32 v34, 16, v9
	v_and_b32_e32 v35, 0xffff0000, v9
	v_lshlrev_b32_e32 v36, 16, v10
	v_and_b32_e32 v37, 0xffff0000, v10
	v_lshlrev_b32_e32 v38, 16, v11
	v_and_b32_e32 v39, 0xffff0000, v11
	v_lshlrev_b32_e32 v40, 16, v12
	v_and_b32_e32 v41, 0xffff0000, v12
	v_lshlrev_b32_e32 v42, 16, v13
	v_and_b32_e32 v43, 0xffff0000, v13
	v_lshlrev_b32_e32 v44, 16, v14
	v_and_b32_e32 v45, 0xffff0000, v14
	v_lshlrev_b32_e32 v46, 16, v15
	v_and_b32_e32 v47, 0xffff0000, v15
	s_nop 1
	v_mfma_f32_16x16x4_f32 v[80:83], v16, v48, 0
	v_mfma_f32_16x16x4_f32 v[84:87], v16, v64, 0
	v_mfma_f32_16x16x4_f32 v[88:91], v32, v48, 0
	v_mfma_f32_16x16x4_f32 v[92:95], v32, v64, 0
	v_mfma_f32_16x16x4_f32 v[80:83], v17, v49, v[80:83]
	v_mfma_f32_16x16x4_f32 v[84:87], v17, v65, v[84:87]
	v_mfma_f32_16x16x4_f32 v[88:91], v33, v49, v[88:91]
	v_mfma_f32_16x16x4_f32 v[92:95], v33, v65, v[92:95]
	v_mfma_f32_16x16x4_f32 v[80:83], v18, v50, v[80:83]
	v_mfma_f32_16x16x4_f32 v[84:87], v18, v66, v[84:87]
	v_mfma_f32_16x16x4_f32 v[88:91], v34, v50, v[88:91]
	v_mfma_f32_16x16x4_f32 v[92:95], v34, v66, v[92:95]
	v_mfma_f32_16x16x4_f32 v[80:83], v19, v51, v[80:83]
	v_mfma_f32_16x16x4_f32 v[84:87], v19, v67, v[84:87]
	v_mfma_f32_16x16x4_f32 v[88:91], v35, v51, v[88:91]
	v_mfma_f32_16x16x4_f32 v[92:95], v35, v67, v[92:95]
	v_mfma_f32_16x16x4_f32 v[80:83], v20, v52, v[80:83]
	v_mfma_f32_16x16x4_f32 v[84:87], v20, v68, v[84:87]
	v_mfma_f32_16x16x4_f32 v[88:91], v36, v52, v[88:91]
	v_mfma_f32_16x16x4_f32 v[92:95], v36, v68, v[92:95]
	v_mfma_f32_16x16x4_f32 v[80:83], v21, v53, v[80:83]
	v_mfma_f32_16x16x4_f32 v[84:87], v21, v69, v[84:87]
	v_mfma_f32_16x16x4_f32 v[88:91], v37, v53, v[88:91]
	v_mfma_f32_16x16x4_f32 v[92:95], v37, v69, v[92:95]
	v_mfma_f32_16x16x4_f32 v[80:83], v22, v54, v[80:83]
	v_mfma_f32_16x16x4_f32 v[84:87], v22, v70, v[84:87]
	v_mfma_f32_16x16x4_f32 v[88:91], v38, v54, v[88:91]
	v_mfma_f32_16x16x4_f32 v[92:95], v38, v70, v[92:95]
	v_mfma_f32_16x16x4_f32 v[80:83], v23, v55, v[80:83]
	v_mfma_f32_16x16x4_f32 v[84:87], v23, v71, v[84:87]
	v_mfma_f32_16x16x4_f32 v[88:91], v39, v55, v[88:91]
	v_mfma_f32_16x16x4_f32 v[92:95], v39, v71, v[92:95]
	v_mfma_f32_16x16x4_f32 v[80:83], v24, v56, v[80:83]
	v_mfma_f32_16x16x4_f32 v[84:87], v24, v72, v[84:87]
	v_mfma_f32_16x16x4_f32 v[88:91], v40, v56, v[88:91]
	v_mfma_f32_16x16x4_f32 v[92:95], v40, v72, v[92:95]
	v_mfma_f32_16x16x4_f32 v[80:83], v25, v57, v[80:83]
	v_mfma_f32_16x16x4_f32 v[84:87], v25, v73, v[84:87]
	v_mfma_f32_16x16x4_f32 v[88:91], v41, v57, v[88:91]
	v_mfma_f32_16x16x4_f32 v[92:95], v41, v73, v[92:95]
	v_mfma_f32_16x16x4_f32 v[80:83], v26, v58, v[80:83]
	v_mfma_f32_16x16x4_f32 v[84:87], v26, v74, v[84:87]
	v_mfma_f32_16x16x4_f32 v[88:91], v42, v58, v[88:91]
	v_mfma_f32_16x16x4_f32 v[92:95], v42, v74, v[92:95]
	v_mfma_f32_16x16x4_f32 v[80:83], v27, v59, v[80:83]
	v_mfma_f32_16x16x4_f32 v[84:87], v27, v75, v[84:87]
	v_mfma_f32_16x16x4_f32 v[88:91], v43, v59, v[88:91]
	v_mfma_f32_16x16x4_f32 v[92:95], v43, v75, v[92:95]
	v_mfma_f32_16x16x4_f32 v[80:83], v28, v60, v[80:83]
	v_mfma_f32_16x16x4_f32 v[84:87], v28, v76, v[84:87]
	v_mfma_f32_16x16x4_f32 v[88:91], v44, v60, v[88:91]
	v_mfma_f32_16x16x4_f32 v[92:95], v44, v76, v[92:95]
	v_mfma_f32_16x16x4_f32 v[80:83], v29, v61, v[80:83]
	v_mfma_f32_16x16x4_f32 v[84:87], v29, v77, v[84:87]
	v_mfma_f32_16x16x4_f32 v[88:91], v45, v61, v[88:91]
	v_mfma_f32_16x16x4_f32 v[92:95], v45, v77, v[92:95]
	v_mfma_f32_16x16x4_f32 v[80:83], v30, v62, v[80:83]
	v_mfma_f32_16x16x4_f32 v[84:87], v30, v78, v[84:87]
	v_mfma_f32_16x16x4_f32 v[88:91], v46, v62, v[88:91]
	v_mfma_f32_16x16x4_f32 v[92:95], v46, v78, v[92:95]
	v_mfma_f32_16x16x4_f32 v[80:83], v31, v63, v[80:83]
	v_mfma_f32_16x16x4_f32 v[84:87], v31, v79, v[84:87]
	v_mfma_f32_16x16x4_f32 v[88:91], v47, v63, v[88:91]
	v_mfma_f32_16x16x4_f32 v[92:95], v47, v79, v[92:95]
	v_lshlrev_b32_e32 v104, 11, v97
	v_lshl_add_u32 v104, v96, 4, v104
	s_nop 10
	ds_write_b128 v104, v[80:83] offset:0
	ds_write_b128 v104, v[84:87] offset:16384
	ds_write_b128 v104, v[88:91] offset:1024
	ds_write_b128 v104, v[92:95] offset:17408
	s_waitcnt lgkmcnt(0)
	s_barrier
	s_lshl_b32 s8, s3, 7
	v_lshl_add_u32 v105, v97, 4, v98
	v_add_u32_e32 v105, s8, v105
	v_lshlrev_b32_e32 v106, 2, v99
	v_add_u32_e32 v107, 0, v106
	v_mul_u32_u24_e32 v108, v107, v105
	v_lshlrev_b32_e32 v108, 2, v108
	v_add_u32_e32 v107, 1, v106
	v_mul_u32_u24_e32 v109, v107, v105
	v_lshlrev_b32_e32 v109, 2, v109
	v_add_u32_e32 v107, 2, v106
	v_mul_u32_u24_e32 v110, v107, v105
	v_lshlrev_b32_e32 v110, 2, v110
	v_add_u32_e32 v107, 3, v106
	v_mul_u32_u24_e32 v111, v107, v105
	v_lshlrev_b32_e32 v111, 2, v111
	v_lshlrev_b32_e32 v112, 6, v105
	v_lshlrev_b32_e32 v113, 4, v96
	s_movk_i32 s9, 0x3fc
	ds_read_b128 v[0:3], v113 offset:0
	ds_read_b128 v[4:7], v113 offset:16384
	v_and_or_b32 v114, v108, s9, v119
	ds_read_b32 v8, v114 offset:512
	ds_read_b32 v12, v114 offset:1536
	v_add_u32_e32 v108, v108, v112
	v_and_or_b32 v114, v109, s9, v119
	ds_read_b32 v9, v114 offset:512
	ds_read_b32 v13, v114 offset:1536
	v_add_u32_e32 v109, v109, v112
	v_and_or_b32 v114, v110, s9, v119
	ds_read_b32 v10, v114 offset:512
	ds_read_b32 v14, v114 offset:1536
	v_add_u32_e32 v110, v110, v112
	v_and_or_b32 v114, v111, s9, v119
	ds_read_b32 v11, v114 offset:512
	ds_read_b32 v15, v114 offset:1536
	v_add_u32_e32 v111, v111, v112
	s_waitcnt lgkmcnt(0)
	ds_read_b128 v[16:19], v113 offset:1024
	ds_read_b128 v[20:23], v113 offset:17408
	v_and_or_b32 v114, v108, s9, v119
	ds_read_b32 v24, v114 offset:512
	ds_read_b32 v28, v114 offset:1536
	v_add_u32_e32 v108, v108, v112
	v_and_or_b32 v114, v109, s9, v119
	ds_read_b32 v25, v114 offset:512
	ds_read_b32 v29, v114 offset:1536
	v_add_u32_e32 v109, v109, v112
	v_and_or_b32 v114, v110, s9, v119
	ds_read_b32 v26, v114 offset:512
	ds_read_b32 v30, v114 offset:1536
	v_add_u32_e32 v110, v110, v112
	v_and_or_b32 v114, v111, s9, v119
	ds_read_b32 v27, v114 offset:512
	ds_read_b32 v31, v114 offset:1536
	v_add_u32_e32 v111, v111, v112
	v_mfma_f32_16x16x4_f32 v[120:123], v0, v8, 0
	v_mfma_f32_16x16x4_f32 v[124:127], v4, v12, 0
	v_mfma_f32_16x16x4_f32 v[120:123], v1, v9, v[120:123]
	v_mfma_f32_16x16x4_f32 v[124:127], v5, v13, v[124:127]
	v_mfma_f32_16x16x4_f32 v[120:123], v2, v10, v[120:123]
	v_mfma_f32_16x16x4_f32 v[124:127], v6, v14, v[124:127]
	v_mfma_f32_16x16x4_f32 v[120:123], v3, v11, v[120:123]
	v_mfma_f32_16x16x4_f32 v[124:127], v7, v15, v[124:127]
	s_waitcnt lgkmcnt(0)
	ds_read_b128 v[0:3], v113 offset:2048
	ds_read_b128 v[4:7], v113 offset:18432
	v_and_or_b32 v114, v108, s9, v119
	ds_read_b32 v8, v114 offset:512
	ds_read_b32 v12, v114 offset:1536
	v_add_u32_e32 v108, v108, v112
	v_and_or_b32 v114, v109, s9, v119
	ds_read_b32 v9, v114 offset:512
	ds_read_b32 v13, v114 offset:1536
	v_add_u32_e32 v109, v109, v112
	v_and_or_b32 v114, v110, s9, v119
	ds_read_b32 v10, v114 offset:512
	ds_read_b32 v14, v114 offset:1536
	v_add_u32_e32 v110, v110, v112
	v_and_or_b32 v114, v111, s9, v119
	ds_read_b32 v11, v114 offset:512
	ds_read_b32 v15, v114 offset:1536
	v_add_u32_e32 v111, v111, v112
	v_mfma_f32_16x16x4_f32 v[120:123], v16, v24, v[120:123]
	v_mfma_f32_16x16x4_f32 v[124:127], v20, v28, v[124:127]
	v_mfma_f32_16x16x4_f32 v[120:123], v17, v25, v[120:123]
	v_mfma_f32_16x16x4_f32 v[124:127], v21, v29, v[124:127]
	v_mfma_f32_16x16x4_f32 v[120:123], v18, v26, v[120:123]
	v_mfma_f32_16x16x4_f32 v[124:127], v22, v30, v[124:127]
	v_mfma_f32_16x16x4_f32 v[120:123], v19, v27, v[120:123]
	v_mfma_f32_16x16x4_f32 v[124:127], v23, v31, v[124:127]
	s_waitcnt lgkmcnt(0)
	ds_read_b128 v[16:19], v113 offset:3072
	ds_read_b128 v[20:23], v113 offset:19456
	v_and_or_b32 v114, v108, s9, v119
	ds_read_b32 v24, v114 offset:512
	ds_read_b32 v28, v114 offset:1536
	v_add_u32_e32 v108, v108, v112
	v_and_or_b32 v114, v109, s9, v119
	ds_read_b32 v25, v114 offset:512
	ds_read_b32 v29, v114 offset:1536
	v_add_u32_e32 v109, v109, v112
	v_and_or_b32 v114, v110, s9, v119
	ds_read_b32 v26, v114 offset:512
	ds_read_b32 v30, v114 offset:1536
	v_add_u32_e32 v110, v110, v112
	v_and_or_b32 v114, v111, s9, v119
	ds_read_b32 v27, v114 offset:512
	ds_read_b32 v31, v114 offset:1536
	v_add_u32_e32 v111, v111, v112
	v_mfma_f32_16x16x4_f32 v[120:123], v0, v8, v[120:123]
	v_mfma_f32_16x16x4_f32 v[124:127], v4, v12, v[124:127]
	v_mfma_f32_16x16x4_f32 v[120:123], v1, v9, v[120:123]
	v_mfma_f32_16x16x4_f32 v[124:127], v5, v13, v[124:127]
	v_mfma_f32_16x16x4_f32 v[120:123], v2, v10, v[120:123]
	v_mfma_f32_16x16x4_f32 v[124:127], v6, v14, v[124:127]
	v_mfma_f32_16x16x4_f32 v[120:123], v3, v11, v[120:123]
	v_mfma_f32_16x16x4_f32 v[124:127], v7, v15, v[124:127]
	s_waitcnt lgkmcnt(0)
	ds_read_b128 v[0:3], v113 offset:4096
	ds_read_b128 v[4:7], v113 offset:20480
	v_and_or_b32 v114, v108, s9, v119
	ds_read_b32 v8, v114 offset:512
	ds_read_b32 v12, v114 offset:1536
	v_add_u32_e32 v108, v108, v112
	v_and_or_b32 v114, v109, s9, v119
	ds_read_b32 v9, v114 offset:512
	ds_read_b32 v13, v114 offset:1536
	v_add_u32_e32 v109, v109, v112
	v_and_or_b32 v114, v110, s9, v119
	ds_read_b32 v10, v114 offset:512
	ds_read_b32 v14, v114 offset:1536
	v_add_u32_e32 v110, v110, v112
	v_and_or_b32 v114, v111, s9, v119
	ds_read_b32 v11, v114 offset:512
	ds_read_b32 v15, v114 offset:1536
	v_add_u32_e32 v111, v111, v112
	v_mfma_f32_16x16x4_f32 v[120:123], v16, v24, v[120:123]
	v_mfma_f32_16x16x4_f32 v[124:127], v20, v28, v[124:127]
	v_mfma_f32_16x16x4_f32 v[120:123], v17, v25, v[120:123]
	v_mfma_f32_16x16x4_f32 v[124:127], v21, v29, v[124:127]
	v_mfma_f32_16x16x4_f32 v[120:123], v18, v26, v[120:123]
	v_mfma_f32_16x16x4_f32 v[124:127], v22, v30, v[124:127]
	v_mfma_f32_16x16x4_f32 v[120:123], v19, v27, v[120:123]
	v_mfma_f32_16x16x4_f32 v[124:127], v23, v31, v[124:127]
	s_waitcnt lgkmcnt(0)
	ds_read_b128 v[16:19], v113 offset:5120
	ds_read_b128 v[20:23], v113 offset:21504
	v_and_or_b32 v114, v108, s9, v119
	ds_read_b32 v24, v114 offset:512
	ds_read_b32 v28, v114 offset:1536
	v_add_u32_e32 v108, v108, v112
	v_and_or_b32 v114, v109, s9, v119
	ds_read_b32 v25, v114 offset:512
	ds_read_b32 v29, v114 offset:1536
	v_add_u32_e32 v109, v109, v112
	v_and_or_b32 v114, v110, s9, v119
	ds_read_b32 v26, v114 offset:512
	ds_read_b32 v30, v114 offset:1536
	v_add_u32_e32 v110, v110, v112
	v_and_or_b32 v114, v111, s9, v119
	ds_read_b32 v27, v114 offset:512
	ds_read_b32 v31, v114 offset:1536
	v_add_u32_e32 v111, v111, v112
	v_mfma_f32_16x16x4_f32 v[120:123], v0, v8, v[120:123]
	v_mfma_f32_16x16x4_f32 v[124:127], v4, v12, v[124:127]
	v_mfma_f32_16x16x4_f32 v[120:123], v1, v9, v[120:123]
	v_mfma_f32_16x16x4_f32 v[124:127], v5, v13, v[124:127]
	v_mfma_f32_16x16x4_f32 v[120:123], v2, v10, v[120:123]
	v_mfma_f32_16x16x4_f32 v[124:127], v6, v14, v[124:127]
	v_mfma_f32_16x16x4_f32 v[120:123], v3, v11, v[120:123]
	v_mfma_f32_16x16x4_f32 v[124:127], v7, v15, v[124:127]
	s_waitcnt lgkmcnt(0)
	ds_read_b128 v[0:3], v113 offset:6144
	ds_read_b128 v[4:7], v113 offset:22528
	v_and_or_b32 v114, v108, s9, v119
	ds_read_b32 v8, v114 offset:512
	ds_read_b32 v12, v114 offset:1536
	v_add_u32_e32 v108, v108, v112
	v_and_or_b32 v114, v109, s9, v119
	ds_read_b32 v9, v114 offset:512
	ds_read_b32 v13, v114 offset:1536
	v_add_u32_e32 v109, v109, v112
	v_and_or_b32 v114, v110, s9, v119
	ds_read_b32 v10, v114 offset:512
	ds_read_b32 v14, v114 offset:1536
	v_add_u32_e32 v110, v110, v112
	v_and_or_b32 v114, v111, s9, v119
	ds_read_b32 v11, v114 offset:512
	ds_read_b32 v15, v114 offset:1536
	v_add_u32_e32 v111, v111, v112
	v_mfma_f32_16x16x4_f32 v[120:123], v16, v24, v[120:123]
	v_mfma_f32_16x16x4_f32 v[124:127], v20, v28, v[124:127]
	v_mfma_f32_16x16x4_f32 v[120:123], v17, v25, v[120:123]
	v_mfma_f32_16x16x4_f32 v[124:127], v21, v29, v[124:127]
	v_mfma_f32_16x16x4_f32 v[120:123], v18, v26, v[120:123]
	v_mfma_f32_16x16x4_f32 v[124:127], v22, v30, v[124:127]
	v_mfma_f32_16x16x4_f32 v[120:123], v19, v27, v[120:123]
	v_mfma_f32_16x16x4_f32 v[124:127], v23, v31, v[124:127]
	s_waitcnt lgkmcnt(0)
	ds_read_b128 v[16:19], v113 offset:7168
	ds_read_b128 v[20:23], v113 offset:23552
	v_and_or_b32 v114, v108, s9, v119
	ds_read_b32 v24, v114 offset:512
	ds_read_b32 v28, v114 offset:1536
	v_add_u32_e32 v108, v108, v112
	v_and_or_b32 v114, v109, s9, v119
	ds_read_b32 v25, v114 offset:512
	ds_read_b32 v29, v114 offset:1536
	v_add_u32_e32 v109, v109, v112
	v_and_or_b32 v114, v110, s9, v119
	ds_read_b32 v26, v114 offset:512
	ds_read_b32 v30, v114 offset:1536
	v_add_u32_e32 v110, v110, v112
	v_and_or_b32 v114, v111, s9, v119
	ds_read_b32 v27, v114 offset:512
	ds_read_b32 v31, v114 offset:1536
	v_add_u32_e32 v111, v111, v112
	v_mfma_f32_16x16x4_f32 v[120:123], v0, v8, v[120:123]
	v_mfma_f32_16x16x4_f32 v[124:127], v4, v12, v[124:127]
	v_mfma_f32_16x16x4_f32 v[120:123], v1, v9, v[120:123]
	v_mfma_f32_16x16x4_f32 v[124:127], v5, v13, v[124:127]
	v_mfma_f32_16x16x4_f32 v[120:123], v2, v10, v[120:123]
	v_mfma_f32_16x16x4_f32 v[124:127], v6, v14, v[124:127]
	v_mfma_f32_16x16x4_f32 v[120:123], v3, v11, v[120:123]
	v_mfma_f32_16x16x4_f32 v[124:127], v7, v15, v[124:127]
	s_waitcnt lgkmcnt(0)
	ds_read_b128 v[0:3], v113 offset:8192
	ds_read_b128 v[4:7], v113 offset:24576
	v_and_or_b32 v114, v108, s9, v119
	ds_read_b32 v8, v114 offset:512
	ds_read_b32 v12, v114 offset:1536
	v_add_u32_e32 v108, v108, v112
	v_and_or_b32 v114, v109, s9, v119
	ds_read_b32 v9, v114 offset:512
	ds_read_b32 v13, v114 offset:1536
	v_add_u32_e32 v109, v109, v112
	v_and_or_b32 v114, v110, s9, v119
	ds_read_b32 v10, v114 offset:512
	ds_read_b32 v14, v114 offset:1536
	v_add_u32_e32 v110, v110, v112
	v_and_or_b32 v114, v111, s9, v119
	ds_read_b32 v11, v114 offset:512
	ds_read_b32 v15, v114 offset:1536
	v_add_u32_e32 v111, v111, v112
	v_mfma_f32_16x16x4_f32 v[120:123], v16, v24, v[120:123]
	v_mfma_f32_16x16x4_f32 v[124:127], v20, v28, v[124:127]
	v_mfma_f32_16x16x4_f32 v[120:123], v17, v25, v[120:123]
	v_mfma_f32_16x16x4_f32 v[124:127], v21, v29, v[124:127]
	v_mfma_f32_16x16x4_f32 v[120:123], v18, v26, v[120:123]
	v_mfma_f32_16x16x4_f32 v[124:127], v22, v30, v[124:127]
	v_mfma_f32_16x16x4_f32 v[120:123], v19, v27, v[120:123]
	v_mfma_f32_16x16x4_f32 v[124:127], v23, v31, v[124:127]
	s_waitcnt lgkmcnt(0)
	ds_read_b128 v[16:19], v113 offset:9216
	ds_read_b128 v[20:23], v113 offset:25600
	v_and_or_b32 v114, v108, s9, v119
	ds_read_b32 v24, v114 offset:512
	ds_read_b32 v28, v114 offset:1536
	v_add_u32_e32 v108, v108, v112
	v_and_or_b32 v114, v109, s9, v119
	ds_read_b32 v25, v114 offset:512
	ds_read_b32 v29, v114 offset:1536
	v_add_u32_e32 v109, v109, v112
	v_and_or_b32 v114, v110, s9, v119
	ds_read_b32 v26, v114 offset:512
	ds_read_b32 v30, v114 offset:1536
	v_add_u32_e32 v110, v110, v112
	v_and_or_b32 v114, v111, s9, v119
	ds_read_b32 v27, v114 offset:512
	ds_read_b32 v31, v114 offset:1536
	v_add_u32_e32 v111, v111, v112
	v_mfma_f32_16x16x4_f32 v[120:123], v0, v8, v[120:123]
	v_mfma_f32_16x16x4_f32 v[124:127], v4, v12, v[124:127]
	v_mfma_f32_16x16x4_f32 v[120:123], v1, v9, v[120:123]
	v_mfma_f32_16x16x4_f32 v[124:127], v5, v13, v[124:127]
	v_mfma_f32_16x16x4_f32 v[120:123], v2, v10, v[120:123]
	v_mfma_f32_16x16x4_f32 v[124:127], v6, v14, v[124:127]
	v_mfma_f32_16x16x4_f32 v[120:123], v3, v11, v[120:123]
	v_mfma_f32_16x16x4_f32 v[124:127], v7, v15, v[124:127]
	s_waitcnt lgkmcnt(0)
	ds_read_b128 v[0:3], v113 offset:10240
	ds_read_b128 v[4:7], v113 offset:26624
	v_and_or_b32 v114, v108, s9, v119
	ds_read_b32 v8, v114 offset:512
	ds_read_b32 v12, v114 offset:1536
	v_add_u32_e32 v108, v108, v112
	v_and_or_b32 v114, v109, s9, v119
	ds_read_b32 v9, v114 offset:512
	ds_read_b32 v13, v114 offset:1536
	v_add_u32_e32 v109, v109, v112
	v_and_or_b32 v114, v110, s9, v119
	ds_read_b32 v10, v114 offset:512
	ds_read_b32 v14, v114 offset:1536
	v_add_u32_e32 v110, v110, v112
	v_and_or_b32 v114, v111, s9, v119
	ds_read_b32 v11, v114 offset:512
	ds_read_b32 v15, v114 offset:1536
	v_add_u32_e32 v111, v111, v112
	v_mfma_f32_16x16x4_f32 v[120:123], v16, v24, v[120:123]
	v_mfma_f32_16x16x4_f32 v[124:127], v20, v28, v[124:127]
	v_mfma_f32_16x16x4_f32 v[120:123], v17, v25, v[120:123]
	v_mfma_f32_16x16x4_f32 v[124:127], v21, v29, v[124:127]
	v_mfma_f32_16x16x4_f32 v[120:123], v18, v26, v[120:123]
	v_mfma_f32_16x16x4_f32 v[124:127], v22, v30, v[124:127]
	v_mfma_f32_16x16x4_f32 v[120:123], v19, v27, v[120:123]
	v_mfma_f32_16x16x4_f32 v[124:127], v23, v31, v[124:127]
	s_waitcnt lgkmcnt(0)
	ds_read_b128 v[16:19], v113 offset:11264
	ds_read_b128 v[20:23], v113 offset:27648
	v_and_or_b32 v114, v108, s9, v119
	ds_read_b32 v24, v114 offset:512
	ds_read_b32 v28, v114 offset:1536
	v_add_u32_e32 v108, v108, v112
	v_and_or_b32 v114, v109, s9, v119
	ds_read_b32 v25, v114 offset:512
	ds_read_b32 v29, v114 offset:1536
	v_add_u32_e32 v109, v109, v112
	v_and_or_b32 v114, v110, s9, v119
	ds_read_b32 v26, v114 offset:512
	ds_read_b32 v30, v114 offset:1536
	v_add_u32_e32 v110, v110, v112
	v_and_or_b32 v114, v111, s9, v119
	ds_read_b32 v27, v114 offset:512
	ds_read_b32 v31, v114 offset:1536
	v_add_u32_e32 v111, v111, v112
	v_mfma_f32_16x16x4_f32 v[120:123], v0, v8, v[120:123]
	v_mfma_f32_16x16x4_f32 v[124:127], v4, v12, v[124:127]
	v_mfma_f32_16x16x4_f32 v[120:123], v1, v9, v[120:123]
	v_mfma_f32_16x16x4_f32 v[124:127], v5, v13, v[124:127]
	v_mfma_f32_16x16x4_f32 v[120:123], v2, v10, v[120:123]
	v_mfma_f32_16x16x4_f32 v[124:127], v6, v14, v[124:127]
	v_mfma_f32_16x16x4_f32 v[120:123], v3, v11, v[120:123]
	v_mfma_f32_16x16x4_f32 v[124:127], v7, v15, v[124:127]
	s_waitcnt lgkmcnt(0)
	ds_read_b128 v[0:3], v113 offset:12288
	ds_read_b128 v[4:7], v113 offset:28672
	v_and_or_b32 v114, v108, s9, v119
	ds_read_b32 v8, v114 offset:512
	ds_read_b32 v12, v114 offset:1536
	v_add_u32_e32 v108, v108, v112
	v_and_or_b32 v114, v109, s9, v119
	ds_read_b32 v9, v114 offset:512
	ds_read_b32 v13, v114 offset:1536
	v_add_u32_e32 v109, v109, v112
	v_and_or_b32 v114, v110, s9, v119
	ds_read_b32 v10, v114 offset:512
	ds_read_b32 v14, v114 offset:1536
	v_add_u32_e32 v110, v110, v112
	v_and_or_b32 v114, v111, s9, v119
	ds_read_b32 v11, v114 offset:512
	ds_read_b32 v15, v114 offset:1536
	v_add_u32_e32 v111, v111, v112
	v_mfma_f32_16x16x4_f32 v[120:123], v16, v24, v[120:123]
	v_mfma_f32_16x16x4_f32 v[124:127], v20, v28, v[124:127]
	v_mfma_f32_16x16x4_f32 v[120:123], v17, v25, v[120:123]
	v_mfma_f32_16x16x4_f32 v[124:127], v21, v29, v[124:127]
	v_mfma_f32_16x16x4_f32 v[120:123], v18, v26, v[120:123]
	v_mfma_f32_16x16x4_f32 v[124:127], v22, v30, v[124:127]
	v_mfma_f32_16x16x4_f32 v[120:123], v19, v27, v[120:123]
	v_mfma_f32_16x16x4_f32 v[124:127], v23, v31, v[124:127]
	s_waitcnt lgkmcnt(0)
	ds_read_b128 v[16:19], v113 offset:13312
	ds_read_b128 v[20:23], v113 offset:29696
	v_and_or_b32 v114, v108, s9, v119
	ds_read_b32 v24, v114 offset:512
	ds_read_b32 v28, v114 offset:1536
	v_add_u32_e32 v108, v108, v112
	v_and_or_b32 v114, v109, s9, v119
	ds_read_b32 v25, v114 offset:512
	ds_read_b32 v29, v114 offset:1536
	v_add_u32_e32 v109, v109, v112
	v_and_or_b32 v114, v110, s9, v119
	ds_read_b32 v26, v114 offset:512
	ds_read_b32 v30, v114 offset:1536
	v_add_u32_e32 v110, v110, v112
	v_and_or_b32 v114, v111, s9, v119
	ds_read_b32 v27, v114 offset:512
	ds_read_b32 v31, v114 offset:1536
	v_add_u32_e32 v111, v111, v112
	v_mfma_f32_16x16x4_f32 v[120:123], v0, v8, v[120:123]
	v_mfma_f32_16x16x4_f32 v[124:127], v4, v12, v[124:127]
	v_mfma_f32_16x16x4_f32 v[120:123], v1, v9, v[120:123]
	v_mfma_f32_16x16x4_f32 v[124:127], v5, v13, v[124:127]
	v_mfma_f32_16x16x4_f32 v[120:123], v2, v10, v[120:123]
	v_mfma_f32_16x16x4_f32 v[124:127], v6, v14, v[124:127]
	v_mfma_f32_16x16x4_f32 v[120:123], v3, v11, v[120:123]
	v_mfma_f32_16x16x4_f32 v[124:127], v7, v15, v[124:127]
	s_waitcnt lgkmcnt(0)
	ds_read_b128 v[0:3], v113 offset:14336
	ds_read_b128 v[4:7], v113 offset:30720
	v_and_or_b32 v114, v108, s9, v119
	ds_read_b32 v8, v114 offset:512
	ds_read_b32 v12, v114 offset:1536
	v_add_u32_e32 v108, v108, v112
	v_and_or_b32 v114, v109, s9, v119
	ds_read_b32 v9, v114 offset:512
	ds_read_b32 v13, v114 offset:1536
	v_add_u32_e32 v109, v109, v112
	v_and_or_b32 v114, v110, s9, v119
	ds_read_b32 v10, v114 offset:512
	ds_read_b32 v14, v114 offset:1536
	v_add_u32_e32 v110, v110, v112
	v_and_or_b32 v114, v111, s9, v119
	ds_read_b32 v11, v114 offset:512
	ds_read_b32 v15, v114 offset:1536
	v_add_u32_e32 v111, v111, v112
	v_mfma_f32_16x16x4_f32 v[120:123], v16, v24, v[120:123]
	v_mfma_f32_16x16x4_f32 v[124:127], v20, v28, v[124:127]
	v_mfma_f32_16x16x4_f32 v[120:123], v17, v25, v[120:123]
	v_mfma_f32_16x16x4_f32 v[124:127], v21, v29, v[124:127]
	v_mfma_f32_16x16x4_f32 v[120:123], v18, v26, v[120:123]
	v_mfma_f32_16x16x4_f32 v[124:127], v22, v30, v[124:127]
	v_mfma_f32_16x16x4_f32 v[120:123], v19, v27, v[120:123]
	v_mfma_f32_16x16x4_f32 v[124:127], v23, v31, v[124:127]
	s_waitcnt lgkmcnt(0)
	ds_read_b128 v[16:19], v113 offset:15360
	ds_read_b128 v[20:23], v113 offset:31744
	v_and_or_b32 v114, v108, s9, v119
	ds_read_b32 v24, v114 offset:512
	ds_read_b32 v28, v114 offset:1536
	v_add_u32_e32 v108, v108, v112
	v_and_or_b32 v114, v109, s9, v119
	ds_read_b32 v25, v114 offset:512
	ds_read_b32 v29, v114 offset:1536
	v_add_u32_e32 v109, v109, v112
	v_and_or_b32 v114, v110, s9, v119
	ds_read_b32 v26, v114 offset:512
	ds_read_b32 v30, v114 offset:1536
	v_add_u32_e32 v110, v110, v112
	v_and_or_b32 v114, v111, s9, v119
	ds_read_b32 v27, v114 offset:512
	ds_read_b32 v31, v114 offset:1536
	v_add_u32_e32 v111, v111, v112
	v_mfma_f32_16x16x4_f32 v[120:123], v0, v8, v[120:123]
	v_mfma_f32_16x16x4_f32 v[124:127], v4, v12, v[124:127]
	v_mfma_f32_16x16x4_f32 v[120:123], v1, v9, v[120:123]
	v_mfma_f32_16x16x4_f32 v[124:127], v5, v13, v[124:127]
	v_mfma_f32_16x16x4_f32 v[120:123], v2, v10, v[120:123]
	v_mfma_f32_16x16x4_f32 v[124:127], v6, v14, v[124:127]
	v_mfma_f32_16x16x4_f32 v[120:123], v3, v11, v[120:123]
	v_mfma_f32_16x16x4_f32 v[124:127], v7, v15, v[124:127]
	s_waitcnt lgkmcnt(0)
	v_mfma_f32_16x16x4_f32 v[120:123], v16, v24, v[120:123]
	v_mfma_f32_16x16x4_f32 v[124:127], v20, v28, v[124:127]
	v_mfma_f32_16x16x4_f32 v[120:123], v17, v25, v[120:123]
	v_mfma_f32_16x16x4_f32 v[124:127], v21, v29, v[124:127]
	v_mfma_f32_16x16x4_f32 v[120:123], v18, v26, v[120:123]
	v_mfma_f32_16x16x4_f32 v[124:127], v22, v30, v[124:127]
	v_mfma_f32_16x16x4_f32 v[120:123], v19, v27, v[120:123]
	v_mfma_f32_16x16x4_f32 v[124:127], v23, v31, v[124:127]
	s_lshl_b32 s6, s0, 17
	s_lshl_b32 s7, s1, 7
	s_add_i32 s6, s6, s7
	s_lshl_b32 s7, s2, 5
	s_add_i32 s6, s6, s7
	s_add_u32 s6, s6, 0xbc00000
	s_add_u32 s6, s4, s6
	s_addc_u32 s7, s5, 0
	v_lshlrev_b32_e32 v115, 9, v105
	v_lshl_add_u32 v115, v99, 3, v115
	s_nop 10
	v_sub_f32_e32 v120, v120, v124
	v_mul_f32_e32 v120, 0x3c000000, v120
	v_sub_f32_e32 v121, v121, v125
	v_mul_f32_e32 v121, 0x3c000000, v121
	v_sub_f32_e32 v122, v122, v126
	v_mul_f32_e32 v122, 0x3c000000, v122
	v_sub_f32_e32 v123, v123, v127
	v_mul_f32_e32 v123, 0x3c000000, v123
	v_bfe_u32 v116, v120, 16, 1
	v_bfe_u32 v117, v121, 16, 1
	v_add3_u32 v116, v120, v116, s77
	v_add3_u32 v117, v121, v117, s77
	v_lshrrev_b32_e32 v116, 16, v116
	v_and_or_b32 v118, v117, s35, v116
	v_bfe_u32 v116, v122, 16, 1
	v_bfe_u32 v117, v123, 16, 1
	v_add3_u32 v116, v122, v116, s77
	v_add3_u32 v117, v123, v117, s77
	v_lshrrev_b32_e32 v116, 16, v116
	v_and_or_b32 v119, v117, s35, v116
	global_store_dwordx2 v115, v[118:119], s[6:7]
	s_mov_b64 s[0:1], 0
	s_branch .LBB0_345
